# GEMM tile transitions: next unit's row-sum (rstd table) load prefetched before the epilogue, init waits vmcnt(16) instead of draining stores, K-loop entry vmcnt(0) only for the residual kind
# baseline (speedup 1.0000x reference)
.LBB0_229:
	s_mov_b32 s5, 0
	s_mov_b64 s[12:13], 0x100
	v_mov_b64_e32 v[2:3], v[156:157]
	v_mov_b64_e32 v[132:133], v[154:155]
	s_cmp_lg_u32 s84, 0
	s_cbranch_scc1 .Lkl_nowait
	s_waitcnt vmcnt(0)
.Lkl_nowait:
.LBB0_230:
	s_add_i32 s4, s5, 2
	s_add_u32 s62, s76, s12
	s_addc_u32 s78, s77, s13
	s_add_u32 s80, s74, s12
	s_addc_u32 s81, s75, s13
	s_add_i32 s82, 0, 0x10000
	s_cmp_eq_u32 s97, s5
	s_cselect_b32 s79, s71, s78
	s_cselect_b32 s78, s70, s62
	v_add_u32_e32 v0, s82, v188
	s_cselect_b32 s81, s73, s81
	s_cselect_b32 s80, s72, s80
	s_add_i32 s5, 0, 0x14000
	ds_read_b128 v[134:137], v0
	ds_read_b128 v[158:161], v0 offset:1024
	ds_read_b128 v[162:165], v0 offset:2048
	ds_read_b128 v[166:169], v0 offset:3072
	v_add_u32_e32 v0, s5, v188
	ds_read_b128 v[198:201], v0
	ds_read_b128 v[202:205], v0 offset:1024
	ds_read_b128 v[206:209], v0 offset:2048
	ds_read_b128 v[210:213], v0 offset:3072
	v_lshl_add_u64 v[138:139], s[76:77], 0, v[132:133]
	s_add_i32 m0, s90, 0xc000
	ds_read_b128 v[214:217], v192
	ds_read_b128 v[218:221], v192 offset:1024
	ds_read_b128 v[222:225], v192 offset:2048
	ds_read_b128 v[226:229], v192 offset:3072
	ds_read_b128 v[230:233], v192 offset:4096
	ds_read_b128 v[234:237], v192 offset:5120
	ds_read_b128 v[238:241], v192 offset:6144
	ds_read_b128 v[242:245], v192 offset:7168
	global_load_lds_dwordx4 v[138:139], off
	v_lshl_add_u64 v[138:139], s[76:77], 0, v[2:3]
	s_add_i32 m0, s90, 0xe000
	s_nop 0
	global_load_lds_dwordx4 v[138:139], off
	s_waitcnt vmcnt(8)
	s_waitcnt lgkmcnt(0)
	s_barrier
	s_setprio 1
	s_waitcnt lgkmcnt(0)
	v_mfma_f32_16x16x32_bf16 v[4:7], v[134:137], v[214:217], v[4:7]
	v_mfma_f32_16x16x32_bf16 v[8:11], v[162:165], v[214:217], v[8:11]
	v_mfma_f32_16x16x32_bf16 v[20:23], v[134:137], v[222:225], v[20:23]
	v_mfma_f32_16x16x32_bf16 v[24:27], v[162:165], v[222:225], v[24:27]
	v_mfma_f32_16x16x32_bf16 v[36:39], v[134:137], v[230:233], v[36:39]
	v_mfma_f32_16x16x32_bf16 v[40:43], v[162:165], v[230:233], v[40:43]
	v_mfma_f32_16x16x32_bf16 v[52:55], v[134:137], v[238:241], v[52:55]
	v_mfma_f32_16x16x32_bf16 v[56:59], v[162:165], v[238:241], v[56:59]
	v_mfma_f32_16x16x32_bf16 v[4:7], v[158:161], v[218:221], v[4:7]
	v_mfma_f32_16x16x32_bf16 v[8:11], v[166:169], v[218:221], v[8:11]
	v_mfma_f32_16x16x32_bf16 v[20:23], v[158:161], v[226:229], v[20:23]
	v_mfma_f32_16x16x32_bf16 v[24:27], v[166:169], v[226:229], v[24:27]
	v_mfma_f32_16x16x32_bf16 v[36:39], v[158:161], v[234:237], v[36:39]
	v_mfma_f32_16x16x32_bf16 v[40:43], v[166:169], v[234:237], v[40:43]
	v_mfma_f32_16x16x32_bf16 v[52:55], v[158:161], v[242:245], v[52:55]
	v_mfma_f32_16x16x32_bf16 v[56:59], v[166:169], v[242:245], v[56:59]
	s_setprio 0
	s_setprio 1
	v_mfma_f32_16x16x32_bf16 v[12:15], v[198:201], v[214:217], v[12:15]
	v_mfma_f32_16x16x32_bf16 v[16:19], v[206:209], v[214:217], v[16:19]
	v_mfma_f32_16x16x32_bf16 v[28:31], v[198:201], v[222:225], v[28:31]
	v_mfma_f32_16x16x32_bf16 v[32:35], v[206:209], v[222:225], v[32:35]
	v_mfma_f32_16x16x32_bf16 v[44:47], v[198:201], v[230:233], v[44:47]
	v_mfma_f32_16x16x32_bf16 v[48:51], v[206:209], v[230:233], v[48:51]
	v_mfma_f32_16x16x32_bf16 v[60:63], v[198:201], v[238:241], v[60:63]
	v_mfma_f32_16x16x32_bf16 v[64:67], v[206:209], v[238:241], v[64:67]
	v_mfma_f32_16x16x32_bf16 v[12:15], v[202:205], v[218:221], v[12:15]
	v_mfma_f32_16x16x32_bf16 v[16:19], v[210:213], v[218:221], v[16:19]
	v_mfma_f32_16x16x32_bf16 v[28:31], v[202:205], v[226:229], v[28:31]
	v_mfma_f32_16x16x32_bf16 v[32:35], v[210:213], v[226:229], v[32:35]
	v_mfma_f32_16x16x32_bf16 v[44:47], v[202:205], v[234:237], v[44:47]
	v_mfma_f32_16x16x32_bf16 v[48:51], v[210:213], v[234:237], v[48:51]
	v_mfma_f32_16x16x32_bf16 v[60:63], v[202:205], v[242:245], v[60:63]
	v_mfma_f32_16x16x32_bf16 v[64:67], v[210:213], v[242:245], v[64:67]
	s_setprio 0
	s_barrier
	s_add_i32 s62, s82, s89
	v_lshl_add_u64 v[138:139], s[80:81], 0, v[144:145]
	s_mov_b32 m0, s62
	ds_read_b128 v[214:217], v192 offset:16384
	ds_read_b128 v[218:221], v192 offset:17408
	ds_read_b128 v[222:225], v192 offset:18432
	ds_read_b128 v[226:229], v192 offset:19456
	ds_read_b128 v[230:233], v192 offset:20480
	ds_read_b128 v[234:237], v192 offset:21504
	ds_read_b128 v[238:241], v192 offset:22528
	ds_read_b128 v[242:245], v192 offset:23552
	global_load_lds_dwordx4 v[138:139], off
	s_add_i32 m0, s62, 0x2000
	v_lshl_add_u64 v[194:195], s[80:81], 0, v[148:149]
	s_add_u32 s80, s80, s54
	s_addc_u32 s81, s81, s55
	s_add_i32 s5, s5, s89
	global_load_lds_dwordx4 v[194:195], off
	v_lshl_add_u64 v[246:247], s[80:81], 0, v[144:145]
	s_mov_b32 m0, s5
	v_lshl_add_u64 v[248:249], s[80:81], 0, v[148:149]
	global_load_lds_dwordx4 v[246:247], off
	s_add_i32 m0, s5, 0x2000
	v_lshl_add_u64 v[250:251], s[78:79], 0, v[142:143]
	global_load_lds_dwordx4 v[248:249], off
	s_mov_b32 m0, s90
	v_lshl_add_u64 v[180:181], s[78:79], 0, v[146:147]
	global_load_lds_dwordx4 v[250:251], off
	s_mov_b32 m0, s91
	s_nop 0
	global_load_lds_dwordx4 v[180:181], off
	s_waitcnt vmcnt(8)
	s_waitcnt lgkmcnt(0)
	s_barrier
	s_setprio 1
	s_waitcnt lgkmcnt(0)
	v_mfma_f32_16x16x32_bf16 v[68:71], v[134:137], v[214:217], v[68:71]
	v_mfma_f32_16x16x32_bf16 v[72:75], v[162:165], v[214:217], v[72:75]
	v_mfma_f32_16x16x32_bf16 v[84:87], v[134:137], v[222:225], v[84:87]
	v_mfma_f32_16x16x32_bf16 v[88:91], v[162:165], v[222:225], v[88:91]
	v_mfma_f32_16x16x32_bf16 v[100:103], v[134:137], v[230:233], v[100:103]
	v_mfma_f32_16x16x32_bf16 v[104:107], v[162:165], v[230:233], v[104:107]
	v_mfma_f32_16x16x32_bf16 v[116:119], v[134:137], v[238:241], v[116:119]
	v_mfma_f32_16x16x32_bf16 v[120:123], v[162:165], v[238:241], v[120:123]
	v_mfma_f32_16x16x32_bf16 v[68:71], v[158:161], v[218:221], v[68:71]
	v_mfma_f32_16x16x32_bf16 v[72:75], v[166:169], v[218:221], v[72:75]
	v_mfma_f32_16x16x32_bf16 v[84:87], v[158:161], v[226:229], v[84:87]
	v_mfma_f32_16x16x32_bf16 v[88:91], v[166:169], v[226:229], v[88:91]
	v_mfma_f32_16x16x32_bf16 v[100:103], v[158:161], v[234:237], v[100:103]
	v_mfma_f32_16x16x32_bf16 v[104:107], v[166:169], v[234:237], v[104:107]
	v_mfma_f32_16x16x32_bf16 v[116:119], v[158:161], v[242:245], v[116:119]
	v_mfma_f32_16x16x32_bf16 v[120:123], v[166:169], v[242:245], v[120:123]
	s_setprio 0
	s_setprio 1
	v_mfma_f32_16x16x32_bf16 v[76:79], v[198:201], v[214:217], v[76:79]
	v_mfma_f32_16x16x32_bf16 v[80:83], v[206:209], v[214:217], v[80:83]
	v_mfma_f32_16x16x32_bf16 v[92:95], v[198:201], v[222:225], v[92:95]
	v_mfma_f32_16x16x32_bf16 v[96:99], v[206:209], v[222:225], v[96:99]
	v_mfma_f32_16x16x32_bf16 v[108:111], v[198:201], v[230:233], v[108:111]
	v_mfma_f32_16x16x32_bf16 v[112:115], v[206:209], v[230:233], v[112:115]
	v_mfma_f32_16x16x32_bf16 v[124:127], v[198:201], v[238:241], v[124:127]
	v_mfma_f32_16x16x32_bf16 v[128:131], v[206:209], v[238:241], v[128:131]
	v_mfma_f32_16x16x32_bf16 v[76:79], v[202:205], v[218:221], v[76:79]
	v_mfma_f32_16x16x32_bf16 v[80:83], v[210:213], v[218:221], v[80:83]
	v_mfma_f32_16x16x32_bf16 v[92:95], v[202:205], v[226:229], v[92:95]
	v_mfma_f32_16x16x32_bf16 v[96:99], v[210:213], v[226:229], v[96:99]
	v_mfma_f32_16x16x32_bf16 v[108:111], v[202:205], v[234:237], v[108:111]
	v_mfma_f32_16x16x32_bf16 v[112:115], v[210:213], v[234:237], v[112:115]
	v_mfma_f32_16x16x32_bf16 v[124:127], v[202:205], v[242:245], v[124:127]
	v_mfma_f32_16x16x32_bf16 v[128:131], v[210:213], v[242:245], v[128:131]
	s_setprio 0
	s_barrier
	s_add_i32 s5, 0, 0x18000
	v_add_u32_e32 v0, s5, v188
	s_add_i32 s62, 0, 0x1c000
	ds_read_b128 v[134:137], v0
	ds_read_b128 v[158:161], v0 offset:1024
	ds_read_b128 v[162:165], v0 offset:2048
	ds_read_b128 v[166:169], v0 offset:3072
	v_add_u32_e32 v0, s62, v188
	ds_read_b128 v[198:201], v0
	ds_read_b128 v[202:205], v0 offset:1024
	ds_read_b128 v[206:209], v0 offset:2048
	ds_read_b128 v[210:213], v0 offset:3072
	s_add_u32 s78, s78, s54
	s_addc_u32 s79, s79, s55
	s_mov_b32 m0, s92
	v_lshl_add_u64 v[182:183], s[78:79], 0, v[142:143]
	ds_read_b128 v[214:217], v192 offset:32768
	ds_read_b128 v[218:221], v192 offset:33792
	ds_read_b128 v[222:225], v192 offset:34816
	ds_read_b128 v[226:229], v192 offset:35840
	ds_read_b128 v[230:233], v192 offset:36864
	ds_read_b128 v[234:237], v192 offset:37888
	ds_read_b128 v[238:241], v192 offset:38912
	ds_read_b128 v[242:245], v192 offset:39936
	global_load_lds_dwordx4 v[182:183], off
	v_lshl_add_u64 v[182:183], s[78:79], 0, v[146:147]
	s_mov_b32 m0, s93
	s_nop 0
	global_load_lds_dwordx4 v[182:183], off
	s_waitcnt vmcnt(8)
	s_waitcnt lgkmcnt(0)
	s_barrier
	s_setprio 1
	s_waitcnt lgkmcnt(0)
	v_mfma_f32_16x16x32_bf16 v[4:7], v[134:137], v[214:217], v[4:7]
	v_mfma_f32_16x16x32_bf16 v[8:11], v[162:165], v[214:217], v[8:11]
	v_mfma_f32_16x16x32_bf16 v[20:23], v[134:137], v[222:225], v[20:23]
	v_mfma_f32_16x16x32_bf16 v[24:27], v[162:165], v[222:225], v[24:27]
	v_mfma_f32_16x16x32_bf16 v[36:39], v[134:137], v[230:233], v[36:39]
	v_mfma_f32_16x16x32_bf16 v[40:43], v[162:165], v[230:233], v[40:43]
	v_mfma_f32_16x16x32_bf16 v[52:55], v[134:137], v[238:241], v[52:55]
	v_mfma_f32_16x16x32_bf16 v[56:59], v[162:165], v[238:241], v[56:59]
	v_mfma_f32_16x16x32_bf16 v[4:7], v[158:161], v[218:221], v[4:7]
	v_mfma_f32_16x16x32_bf16 v[8:11], v[166:169], v[218:221], v[8:11]
	v_mfma_f32_16x16x32_bf16 v[20:23], v[158:161], v[226:229], v[20:23]
	v_mfma_f32_16x16x32_bf16 v[24:27], v[166:169], v[226:229], v[24:27]
	v_mfma_f32_16x16x32_bf16 v[36:39], v[158:161], v[234:237], v[36:39]
	v_mfma_f32_16x16x32_bf16 v[40:43], v[166:169], v[234:237], v[40:43]
	v_mfma_f32_16x16x32_bf16 v[52:55], v[158:161], v[242:245], v[52:55]
	v_mfma_f32_16x16x32_bf16 v[56:59], v[166:169], v[242:245], v[56:59]
	s_setprio 0
	s_setprio 1
	v_mfma_f32_16x16x32_bf16 v[12:15], v[198:201], v[214:217], v[12:15]
	v_mfma_f32_16x16x32_bf16 v[16:19], v[206:209], v[214:217], v[16:19]
	v_mfma_f32_16x16x32_bf16 v[28:31], v[198:201], v[222:225], v[28:31]
	v_mfma_f32_16x16x32_bf16 v[32:35], v[206:209], v[222:225], v[32:35]
	v_mfma_f32_16x16x32_bf16 v[44:47], v[198:201], v[230:233], v[44:47]
	v_mfma_f32_16x16x32_bf16 v[48:51], v[206:209], v[230:233], v[48:51]
	v_mfma_f32_16x16x32_bf16 v[60:63], v[198:201], v[238:241], v[60:63]
	v_mfma_f32_16x16x32_bf16 v[64:67], v[206:209], v[238:241], v[64:67]
	v_mfma_f32_16x16x32_bf16 v[12:15], v[202:205], v[218:221], v[12:15]
	v_mfma_f32_16x16x32_bf16 v[16:19], v[210:213], v[218:221], v[16:19]
	v_mfma_f32_16x16x32_bf16 v[28:31], v[202:205], v[226:229], v[28:31]
	v_mfma_f32_16x16x32_bf16 v[32:35], v[210:213], v[226:229], v[32:35]
	v_mfma_f32_16x16x32_bf16 v[44:47], v[202:205], v[234:237], v[44:47]
	v_mfma_f32_16x16x32_bf16 v[48:51], v[210:213], v[234:237], v[48:51]
	v_mfma_f32_16x16x32_bf16 v[60:63], v[202:205], v[242:245], v[60:63]
	v_mfma_f32_16x16x32_bf16 v[64:67], v[210:213], v[242:245], v[64:67]
	s_setprio 0
	s_barrier
	s_add_i32 s5, s5, s89
	v_lshl_add_u64 v[138:139], v[138:139], 0, s[56:57]
	s_mov_b32 m0, s5
	ds_read_b128 v[214:217], v192 offset:49152
	ds_read_b128 v[218:221], v192 offset:50176
	ds_read_b128 v[222:225], v192 offset:51200
	ds_read_b128 v[226:229], v192 offset:52224
	ds_read_b128 v[230:233], v192 offset:53248
	ds_read_b128 v[234:237], v192 offset:54272
	ds_read_b128 v[238:241], v192 offset:55296
	ds_read_b128 v[242:245], v192 offset:56320
	global_load_lds_dwordx4 v[138:139], off
	v_lshl_add_u64 v[138:139], v[194:195], 0, s[56:57]
	s_add_i32 m0, s5, 0x2000
	s_add_i32 s5, s62, s89
	global_load_lds_dwordx4 v[138:139], off
	v_lshl_add_u64 v[138:139], v[246:247], 0, s[56:57]
	s_mov_b32 m0, s5
	s_nop 0
	global_load_lds_dwordx4 v[138:139], off
	v_lshl_add_u64 v[138:139], v[248:249], 0, s[56:57]
	s_add_i32 m0, s5, 0x2000
	s_nop 0
	global_load_lds_dwordx4 v[138:139], off
	v_lshl_add_u64 v[138:139], v[250:251], 0, s[56:57]
	s_mov_b32 m0, s94
	s_nop 0
	global_load_lds_dwordx4 v[138:139], off
	v_lshl_add_u64 v[138:139], v[180:181], 0, s[56:57]
	s_mov_b32 m0, s95
	s_nop 0
	global_load_lds_dwordx4 v[138:139], off
	s_waitcnt vmcnt(8)
	s_waitcnt lgkmcnt(0)
	s_barrier
	s_setprio 1
	s_waitcnt lgkmcnt(0)
	v_mfma_f32_16x16x32_bf16 v[68:71], v[134:137], v[214:217], v[68:71]
	v_mfma_f32_16x16x32_bf16 v[72:75], v[162:165], v[214:217], v[72:75]
	v_mfma_f32_16x16x32_bf16 v[84:87], v[134:137], v[222:225], v[84:87]
	v_mfma_f32_16x16x32_bf16 v[88:91], v[162:165], v[222:225], v[88:91]
	v_mfma_f32_16x16x32_bf16 v[100:103], v[134:137], v[230:233], v[100:103]
	v_mfma_f32_16x16x32_bf16 v[104:107], v[162:165], v[230:233], v[104:107]
	v_mfma_f32_16x16x32_bf16 v[116:119], v[134:137], v[238:241], v[116:119]
	v_mfma_f32_16x16x32_bf16 v[120:123], v[162:165], v[238:241], v[120:123]
	v_mfma_f32_16x16x32_bf16 v[68:71], v[158:161], v[218:221], v[68:71]
	v_mfma_f32_16x16x32_bf16 v[72:75], v[166:169], v[218:221], v[72:75]
	v_mfma_f32_16x16x32_bf16 v[84:87], v[158:161], v[226:229], v[84:87]
	v_mfma_f32_16x16x32_bf16 v[88:91], v[166:169], v[226:229], v[88:91]
	v_mfma_f32_16x16x32_bf16 v[100:103], v[158:161], v[234:237], v[100:103]
	v_mfma_f32_16x16x32_bf16 v[104:107], v[166:169], v[234:237], v[104:107]
	v_mfma_f32_16x16x32_bf16 v[116:119], v[158:161], v[242:245], v[116:119]
	v_mfma_f32_16x16x32_bf16 v[120:123], v[166:169], v[242:245], v[120:123]
	s_setprio 0
	s_setprio 1
	v_mfma_f32_16x16x32_bf16 v[76:79], v[198:201], v[214:217], v[76:79]
	v_mfma_f32_16x16x32_bf16 v[80:83], v[206:209], v[214:217], v[80:83]
	v_mfma_f32_16x16x32_bf16 v[92:95], v[198:201], v[222:225], v[92:95]
	v_mfma_f32_16x16x32_bf16 v[96:99], v[206:209], v[222:225], v[96:99]
	v_mfma_f32_16x16x32_bf16 v[108:111], v[198:201], v[230:233], v[108:111]
	v_mfma_f32_16x16x32_bf16 v[112:115], v[206:209], v[230:233], v[112:115]
	v_mfma_f32_16x16x32_bf16 v[124:127], v[198:201], v[238:241], v[124:127]
	v_mfma_f32_16x16x32_bf16 v[128:131], v[206:209], v[238:241], v[128:131]
	v_mfma_f32_16x16x32_bf16 v[76:79], v[202:205], v[218:221], v[76:79]
	v_mfma_f32_16x16x32_bf16 v[80:83], v[210:213], v[218:221], v[80:83]
	v_mfma_f32_16x16x32_bf16 v[92:95], v[202:205], v[226:229], v[92:95]
	v_mfma_f32_16x16x32_bf16 v[96:99], v[210:213], v[226:229], v[96:99]
	v_mfma_f32_16x16x32_bf16 v[108:111], v[202:205], v[234:237], v[108:111]
	v_mfma_f32_16x16x32_bf16 v[112:115], v[210:213], v[234:237], v[112:115]
	v_mfma_f32_16x16x32_bf16 v[124:127], v[202:205], v[242:245], v[124:127]
	v_mfma_f32_16x16x32_bf16 v[128:131], v[210:213], v[242:245], v[128:131]
	s_setprio 0
	s_barrier
	s_add_u32 s12, s12, 0x100
	s_addc_u32 s13, s13, 0
	v_lshl_add_u64 v[132:133], v[132:133], 0, s[42:43]
	v_lshl_add_u64 v[2:3], v[2:3], 0, s[42:43]
	s_cmp_ge_u32 s4, s96
	s_mov_b32 s5, s4
	s_cbranch_scc0 .LBB0_230
	s_and_b64 vcc, exec, s[64:65]
	s_cbranch_vccz .LBB0_233
	s_barrier
.LBB0_233:
	s_and_b64 vcc, exec, s[10:11]
	s_cbranch_vccnz .Lpf_skip
	v_readlane_b32 s4, v254, 27
	v_readlane_b32 s5, v254, 28
	s_and_b64 vcc, exec, s[4:5]
	s_cbranch_vccnz .Lpf_skip
	v_lshl_add_u32 v244, s53, 8, v190
	v_ashrrev_i32_e32 v245, 31, v244
	v_lshl_add_u64 v[244:245], v[244:245], 3, s[26:27]
	global_load_dwordx2 v[244:245], v[244:245], off

.LBB0_336:
	s_and_b64 vcc, exec, s[0:1]
	s_cbranch_vccnz .LBB0_222
	v_readlane_b32 s0, v254, 27
	v_readlane_b32 s1, v254, 28
	s_and_b64 vcc, exec, s[0:1]
	s_mov_b64 s[0:1], -1
	s_cbranch_vccnz .LBB0_341
	s_mov_b64 s[12:13], exec
	v_readlane_b32 s0, v254, 41
	v_readlane_b32 s1, v254, 42
	s_and_b64 s[0:1], s[12:13], s[0:1]
	s_mov_b64 exec, s[0:1]
	s_cbranch_execz .LBB0_340
	s_waitcnt lgkmcnt(0)
	s_waitcnt vmcnt(16)
	v_mov_b32_e32 v2, v244
	v_mov_b32_e32 v3, v245
	v_ffbh_u32_e32 v0, v3
	v_min_u32_e32 v0, 32, v0
	v_lshlrev_b64 v[2:3], v0, v[2:3]
	v_min_u32_e32 v2, 1, v2
	v_or_b32_e32 v2, v3, v2
	v_cvt_f32_u32_e32 v2, v2
	v_sub_u32_e32 v0, 32, v0
	v_ldexp_f32 v0, v2, v0
	v_mul_f32_e32 v0, 0x2f800000, v0
	v_fmamk_f32 v0, v0, 0x3a000000, v171
	v_cmp_gt_f32_e32 vcc, s51, v0
	v_mul_f32_e32 v2, 0x4f800000, v0
	s_nop 0
	v_cndmask_b32_e32 v0, v0, v2, vcc
	v_sqrt_f32_e32 v2, v0
	s_nop 0
	v_add_u32_e32 v3, -1, v2
	v_fma_f32 v4, -v3, v2, v0
	v_cmp_ge_f32_e64 s[0:1], 0, v4
	v_add_u32_e32 v4, 1, v2
	s_nop 0
	v_cndmask_b32_e64 v3, v2, v3, s[0:1]
	v_fma_f32 v2, -v4, v2, v0
	v_cmp_lt_f32_e64 s[0:1], 0, v2
	s_nop 1
	v_cndmask_b32_e64 v2, v3, v4, s[0:1]
	v_mul_f32_e32 v3, 0x37800000, v2
	v_cndmask_b32_e32 v2, v2, v3, vcc
	v_cmp_class_f32_e32 vcc, v0, v172
	s_nop 1
	v_cndmask_b32_e32 v0, v2, v0, vcc
	v_div_scale_f32 v2, s[0:1], v0, v0, 1.0
	v_rcp_f32_e32 v3, v2
	s_lshl_b32 s0, s66, 10
	s_and_b32 s0, s0, 0x400
	v_fma_f32 v4, -v2, v3, 1.0
	v_fmac_f32_e32 v3, v4, v3
	v_div_scale_f32 v4, vcc, 1.0, v0, 1.0
	v_mul_f32_e32 v5, v4, v3
	v_fma_f32 v6, -v2, v5, v4
	v_fmac_f32_e32 v5, v6, v3
	v_fma_f32 v2, -v2, v5, v4
	v_div_fmas_f32 v2, v2, v3, v5
	v_div_fixup_f32 v0, v2, v0, 1.0
	v_add_u32_e32 v2, s0, v191
	ds_write_b32 v2, v0
